# P13 FFT: 6 workgroup barriers removed between passes whose 512-element blocks are owned by a single wave (sl=6/3/0 passes), lgkmcnt waits kept
# speedup vs baseline: 1.0010x; 1.0010x over previous
;     static __device__ __forceinline__ float sl(float g, float up) { return g * __builtin_amdgcn_rcpf(1.0f + __builtin_amdgcn_exp2f(-1.4426950408889634f * g)) * up; }
; #define tid ltid()
; template <int LR, bool INV>
; __device__ __forceinline__ void fft_pass(float2* X, const int N, const int sl, const int tid) {
;   constexpr int R = 1 << LR;
;   const int s = 1 << sl;
;   for (int g = tid; g < (N >> LR); g += NTHR) {
;     const int r = g & (s - 1);
;     const int i0 = ((g >> sl) << (sl + LR)) + r;
;     float2 x[R];
; #pragma unroll
;     for (int m = 0; m < R; ++m) x[m] = X[PIDX(i0 + (m << sl))];
;     fft_stages<LR, INV>(x, r, s);
; #pragma unroll
;     for (int m = 0; m < R; ++m) X[PIDX(i0 + (m << sl))] = x[m];
;   }
;   __syncthreads();
; __device__ __forceinline__ void fft_fwd(float2* X, int N, int tid) {
;     ...
;   fft_pass<3, false>(X, N, 6, tid); fft_pass<3, false>(X, N, 3, tid); fft_pass<3, false>(X, N, 0, tid);
.LBB0_661:
	s_or_b64 exec, exec, s[12:13]
	s_waitcnt lgkmcnt(0)
	s_and_saveexec_b64 s[12:13], vcc
	s_cbranch_execz .LBB0_664
	v_and_b32_e32 v29, 7, v60
	v_cvt_f32_ubyte0_e32 v14, v29
	v_mul_f32_e32 v0, 0x3c800000, v14
	v_sin_f32_e32 v6, v0
	v_cos_f32_e32 v7, v0
	v_mul_f32_e32 v11, 0x3d000000, v14
	v_sin_f32_e32 v10, v11
	v_cos_f32_e32 v11, v11
	v_mul_f32_e32 v15, 0x3d800000, v14
	v_sin_f32_e32 v14, v15
	v_cos_f32_e32 v15, v15
	v_xor_b32_e32 v2, 0x80000000, v6
	v_pk_mov_b32 v[0:1], v[6:7], v[6:7] op_sel:[1,0]
	s_mov_b32 s90, s75
	v_mov_b32_e32 v1, v2
	v_mul_f32_e32 v8, s70, v6
	v_mul_f32_e32 v9, s70, v7
	s_mov_b32 s14, s71
	s_mov_b32 s15, s70
	s_mov_b32 s74, s91
	v_fma_f32 v0, -v6, 0, v0
	v_fma_f32 v1, -v7, 0, v1
	v_fma_f32 v2, v7, s14, v8
	v_fma_f32 v3, v6, s15, v9
	v_fma_f32 v4, v7, s90, -v6
	v_fma_f32 v5, v6, s91, -v7
	v_pk_fma_f32 v[6:7], v[6:7], s[70:71], v[8:9] op_sel:[1,0,0] op_sel_hi:[0,1,1]
	v_xor_b32_e32 v9, 0x80000000, v10
	v_mul_f32_e32 v12, s74, v10
	v_mul_f32_e32 v13, s75, v11
	v_mov_b32_e32 v8, v11
	v_fma_f32 v8, -v10, 0, v8
	v_fma_f32 v9, -v11, 0, v9
	v_sub_f32_e32 v10, v13, v10
	v_sub_f32_e32 v11, v12, v11
	v_xor_b32_e32 v13, 0x80000000, v14
	v_mov_b32_e32 v12, v15
	v_fma_f32 v12, -v14, 0, v12
	v_fma_f32 v13, -v15, 0, v13
	v_pk_mov_b32 v[16:17], v[8:9], v[8:9] op_sel:[1,0]
	v_pk_mov_b32 v[14:15], v[12:13], v[12:13] op_sel:[1,0]
	v_pk_mov_b32 v[18:19], v[10:11], v[10:11] op_sel:[1,0]
	v_pk_mov_b32 v[20:21], v[0:1], v[0:1] op_sel:[1,0]
	v_pk_mov_b32 v[22:23], v[2:3], v[2:3] op_sel:[1,0]
	v_pk_mov_b32 v[24:25], v[4:5], v[4:5] op_sel:[1,0]
	v_pk_mov_b32 v[26:27], v[6:7], v[6:7] op_sel:[1,0]
	v_lshlrev_b32_e32 v30, 3, v60
	s_mov_b64 s[14:15], 0
	v_mov_b32_e32 v31, v60

;     static __device__ __forceinline__ float sl(float g, float up) { return g * __builtin_amdgcn_rcpf(1.0f + __builtin_amdgcn_exp2f(-1.4426950408889634f * g)) * up; }
; #define tid ltid()
; template <int LR, bool INV>
; __device__ __forceinline__ void fft_pass(float2* X, const int N, const int sl, const int tid) {
;   constexpr int R = 1 << LR;
;   const int s = 1 << sl;
;   for (int g = tid; g < (N >> LR); g += NTHR) {
;     const int r = g & (s - 1);
;     const int i0 = ((g >> sl) << (sl + LR)) + r;
;     float2 x[R];
; #pragma unroll
;     for (int m = 0; m < R; ++m) x[m] = X[PIDX(i0 + (m << sl))];
;     fft_stages<LR, INV>(x, r, s);
; #pragma unroll
;     for (int m = 0; m < R; ++m) X[PIDX(i0 + (m << sl))] = x[m];
;   }
;   __syncthreads();
; __device__ __forceinline__ void fft_fwd(float2* X, int N, int tid) {
;     ...
;   fft_pass<3, false>(X, N, 6, tid); fft_pass<3, false>(X, N, 3, tid); fft_pass<3, false>(X, N, 0, tid);
.LBB0_664:
	s_or_b64 exec, exec, s[12:13]
	s_waitcnt lgkmcnt(0)
	s_and_saveexec_b64 s[12:13], vcc
	s_cbranch_execz .LBB0_667
	v_lshl_add_u32 v4, v60, 6, s52
	s_mov_b64 s[14:15], 0

;     static __device__ __forceinline__ float sl(float g, float up) { return g * __builtin_amdgcn_rcpf(1.0f + __builtin_amdgcn_exp2f(-1.4426950408889634f * g)) * up; }
; #define tid ltid()
; template <int LR, bool INV>
; __device__ __forceinline__ void fft_pass(float2* X, const int N, const int sl, const int tid) {
;   constexpr int R = 1 << LR;
;   const int s = 1 << sl;
;   for (int g = tid; g < (N >> LR); g += NTHR) {
;     const int r = g & (s - 1);
;     const int i0 = ((g >> sl) << (sl + LR)) + r;
;     float2 x[R];
; #pragma unroll
;     for (int m = 0; m < R; ++m) x[m] = X[PIDX(i0 + (m << sl))];
;     fft_stages<LR, INV>(x, r, s);
; #pragma unroll
;     for (int m = 0; m < R; ++m) X[PIDX(i0 + (m << sl))] = x[m];
;   }
;   __syncthreads();
; __global__ void __launch_bounds__(NTHR, 2) mega_fwd(Args a_unused) {
;     ...
;             fft_pass<3, false>(A, N, 6, tid); fft_pass<3, false>(A, N, 3, tid);
.LBB0_676:
	s_or_b64 exec, exec, s[12:13]
	v_mov_b32_e32 v30, v208
	s_waitcnt lgkmcnt(0)
	s_nop 0
	v_cmp_gt_i32_e32 vcc, s21, v30
	s_and_saveexec_b64 s[12:13], vcc
	s_cbranch_execz .LBB0_679
	v_and_b32_e32 v31, 7, v30
	v_cvt_f32_ubyte0_e32 v16, v31
	v_mul_f32_e32 v2, 0x3c800000, v16
	v_sin_f32_e32 v8, v2
	v_cos_f32_e32 v9, v2
	v_mul_f32_e32 v13, 0x3d000000, v16
	v_sin_f32_e32 v12, v13
	v_cos_f32_e32 v13, v13
	v_mul_f32_e32 v17, 0x3d800000, v16
	v_sin_f32_e32 v16, v17
	v_cos_f32_e32 v17, v17
	v_xor_b32_e32 v4, 0x80000000, v8
	v_pk_mov_b32 v[2:3], v[8:9], v[8:9] op_sel:[1,0]
	s_mov_b32 s90, s75
	v_mov_b32_e32 v3, v4
	v_mul_f32_e32 v10, s70, v8
	v_mul_f32_e32 v11, s70, v9
	s_mov_b32 s14, s71
	s_mov_b32 s15, s70
	s_mov_b32 s74, s91
	v_fma_f32 v2, -v8, 0, v2
	v_fma_f32 v3, -v9, 0, v3
	v_fma_f32 v4, v9, s14, v10
	v_fma_f32 v5, v8, s15, v11
	v_fma_f32 v6, v9, s90, -v8
	v_fma_f32 v7, v8, s91, -v9
	v_pk_fma_f32 v[8:9], v[8:9], s[70:71], v[10:11] op_sel:[1,0,0] op_sel_hi:[0,1,1]
	v_xor_b32_e32 v11, 0x80000000, v12
	v_mul_f32_e32 v14, s74, v12
	v_mul_f32_e32 v15, s75, v13
	v_mov_b32_e32 v10, v13
	v_fma_f32 v10, -v12, 0, v10
	v_fma_f32 v11, -v13, 0, v11
	v_sub_f32_e32 v12, v15, v12
	v_sub_f32_e32 v13, v14, v13
	v_xor_b32_e32 v15, 0x80000000, v16
	v_mov_b32_e32 v14, v17
	v_fma_f32 v14, -v16, 0, v14
	v_fma_f32 v15, -v17, 0, v15
	v_pk_mov_b32 v[18:19], v[10:11], v[10:11] op_sel:[1,0]
	v_pk_mov_b32 v[16:17], v[14:15], v[14:15] op_sel:[1,0]
	v_pk_mov_b32 v[20:21], v[12:13], v[12:13] op_sel:[1,0]
	v_pk_mov_b32 v[22:23], v[2:3], v[2:3] op_sel:[1,0]
	v_pk_mov_b32 v[24:25], v[4:5], v[4:5] op_sel:[1,0]
	v_pk_mov_b32 v[26:27], v[6:7], v[6:7] op_sel:[1,0]
	v_pk_mov_b32 v[28:29], v[8:9], v[8:9] op_sel:[1,0]
	v_lshlrev_b32_e32 v32, 3, v30
	s_mov_b64 s[14:15], 0

; #define tid ltid()
; __device__ __forceinline__ void fft_mid(float2* X, const float2* Hb, const int N, const float invN, const int tid) {
;   for (int g = tid; g < (N >> 3); g += NTHR) {
;     const int i0 = g << 3; const int p0 = PIDX(i0);
;     float2 x[8];
; #pragma unroll
;     for (int m = 0; m < 8; ++m) x[m] = X[p0 + m];
;     fft_stages<3, false>(x, 0, 1);
; #pragma unroll
;     for (int m = 0; m < 8; ++m) { const float2 h = Hb[p0 + m]; const float2 v = x[m]; x[m] = make_float2((v.x * h.x - v.y * h.y) * invN, (v.x * h.y + v.y * h.x) * invN); }
;     fft_stages<3, true>(x, 0, 1);
; #pragma unroll
;     for (int m = 0; m < 8; ++m) X[p0 + m] = x[m];
;   }
;   __syncthreads();
; __global__ void __launch_bounds__(NTHR, 2) mega_fwd(Args a_unused) {
;     ...
;             fft_pass<3, false>(A, N, 6, tid); fft_pass<3, false>(A, N, 3, tid);
;             fft_mid(A, Hb, N, invN, tid);
.LBB0_679:
	s_or_b64 exec, exec, s[12:13]
	v_mov_b32_e32 v2, v208
	s_waitcnt lgkmcnt(0)
	s_nop 0
	v_cmp_gt_i32_e32 vcc, s21, v2
	s_and_saveexec_b64 s[12:13], vcc
	s_cbranch_execz .LBB0_682
	v_lshlrev_b32_e32 v3, 3, v2
	s_mov_b64 s[14:15], 0

;     static __device__ __forceinline__ float sl(float g, float up) { return g * __builtin_amdgcn_rcpf(1.0f + __builtin_amdgcn_exp2f(-1.4426950408889634f * g)) * up; }
; #define tid ltid()
; template <int LR, bool INV>
; __device__ __forceinline__ void fft_pass(float2* X, const int N, const int sl, const int tid) {
;   constexpr int R = 1 << LR;
;   const int s = 1 << sl;
;   for (int g = tid; g < (N >> LR); g += NTHR) {
;     const int r = g & (s - 1);
;     const int i0 = ((g >> sl) << (sl + LR)) + r;
;     float2 x[R];
; #pragma unroll
;     for (int m = 0; m < R; ++m) x[m] = X[PIDX(i0 + (m << sl))];
;     fft_stages<LR, INV>(x, r, s);
; #pragma unroll
;     for (int m = 0; m < R; ++m) X[PIDX(i0 + (m << sl))] = x[m];
;   }
;   __syncthreads();
; __global__ void __launch_bounds__(NTHR, 2) mega_fwd(Args a_unused) {
;     ...
;             fft_mid(A, Hb, N, invN, tid);
;             fft_pass<3, true>(A, N, 3, tid); fft_pass<3, true>(A, N, 6, tid);
.LBB0_682:
	s_or_b64 exec, exec, s[12:13]
	v_mov_b32_e32 v30, v208
	s_waitcnt lgkmcnt(0)
	s_nop 0
	v_cmp_gt_i32_e32 vcc, s21, v30
	s_and_saveexec_b64 s[12:13], vcc
	s_cbranch_execz .LBB0_685
	v_and_b32_e32 v31, 7, v30
	v_cvt_f32_ubyte0_e32 v3, v31
	v_mul_f32_e32 v2, 0x3d800000, v3
	v_mul_f32_e32 v6, 0x3d000000, v3
	v_mul_f32_e32 v3, 0x3c800000, v3
	v_cos_f32_e32 v24, v3
	v_sin_f32_e32 v3, v3
	v_cos_f32_e32 v5, v2
	v_sin_f32_e32 v2, v2
	v_cos_f32_e32 v4, v6
	v_sin_f32_e32 v7, v6
	v_mul_f32_e32 v26, 0x3f3504f3, v3
	v_mul_f32_e32 v22, 0x3f3504f3, v24
	v_fmamk_f32 v6, v2, 0x80000000, v5
	v_fmac_f32_e32 v2, 0, v5
	v_fmamk_f32 v8, v7, 0x80000000, v4
	v_fma_f32 v10, 0, v4, v7
	v_fma_f32 v12, v4, 0, -v7
	v_fmac_f32_e32 v4, 0, v7
	v_fmamk_f32 v14, v3, 0x80000000, v24
	v_fma_f32 v16, 0, v24, v3
	v_fma_f32 v18, v24, 0, -v3
	v_fma_f32 v20, 0, v3, v24
	v_fmac_f32_e32 v22, 0x3f3504f3, v3
	v_fma_f32 v25, v24, s71, -v26
	v_fma_f32 v24, v24, s70, -v26
	v_mov_b32_e32 v7, v6
	v_mov_b32_e32 v3, v2
	v_mov_b32_e32 v13, v12
	v_mov_b32_e32 v5, v4
	v_mov_b32_e32 v19, v18
	v_mov_b32_e32 v9, v8
	v_mov_b32_e32 v11, v10
	v_mov_b32_e32 v15, v14
	v_mov_b32_e32 v26, v25
	v_mov_b32_e32 v27, v25
	v_mov_b32_e32 v21, v20
	v_mov_b32_e32 v17, v16
	v_mov_b32_e32 v23, v22
	v_pk_mov_b32 v[28:29], v[24:25], v[24:25] op_sel:[1,0]
	v_lshlrev_b32_e32 v32, 3, v30
	s_mov_b64 s[14:15], 0

;     static __device__ __forceinline__ float sl(float g, float up) { return g * __builtin_amdgcn_rcpf(1.0f + __builtin_amdgcn_exp2f(-1.4426950408889634f * g)) * up; }
; #define tid ltid()
; template <int LR, bool INV>
; __device__ __forceinline__ void fft_pass(float2* X, const int N, const int sl, const int tid) {
;   constexpr int R = 1 << LR;
;   const int s = 1 << sl;
;   for (int g = tid; g < (N >> LR); g += NTHR) {
;     const int r = g & (s - 1);
;     const int i0 = ((g >> sl) << (sl + LR)) + r;
;     float2 x[R];
; #pragma unroll
;     for (int m = 0; m < R; ++m) x[m] = X[PIDX(i0 + (m << sl))];
;     fft_stages<LR, INV>(x, r, s);
; #pragma unroll
;     for (int m = 0; m < R; ++m) X[PIDX(i0 + (m << sl))] = x[m];
;   }
;   __syncthreads();
; __global__ void __launch_bounds__(NTHR, 2) mega_fwd(Args a_unused) {
;     ...
;             fft_pass<3, true>(A, N, 3, tid); fft_pass<3, true>(A, N, 6, tid);
.LBB0_685:
	s_or_b64 exec, exec, s[12:13]
	v_mov_b32_e32 v30, v208
	s_waitcnt lgkmcnt(0)
	s_nop 0
	v_cmp_gt_i32_e32 vcc, s21, v30
	s_and_saveexec_b64 s[12:13], vcc
	s_cbranch_execz .LBB0_688
	v_and_b32_e32 v31, 63, v30
	v_cvt_f32_ubyte0_e32 v3, v31
	v_mul_f32_e32 v2, 0x3c000000, v3
	v_mul_f32_e32 v6, 0x3b800000, v3
	v_mul_f32_e32 v3, 0x3b000000, v3
	v_cos_f32_e32 v24, v3
	v_sin_f32_e32 v3, v3
	v_cos_f32_e32 v5, v2
	v_sin_f32_e32 v2, v2
	v_cos_f32_e32 v4, v6
	v_sin_f32_e32 v7, v6
	v_mul_f32_e32 v26, 0x3f3504f3, v3
	v_mul_f32_e32 v22, 0x3f3504f3, v24
	v_fmamk_f32 v6, v2, 0x80000000, v5
	v_fmac_f32_e32 v2, 0, v5
	v_fmamk_f32 v8, v7, 0x80000000, v4
	v_fma_f32 v10, 0, v4, v7
	v_fma_f32 v12, v4, 0, -v7
	v_fmac_f32_e32 v4, 0, v7
	v_fmamk_f32 v14, v3, 0x80000000, v24
	v_fma_f32 v16, 0, v24, v3
	v_fma_f32 v18, v24, 0, -v3
	v_fma_f32 v20, 0, v3, v24
	v_fmac_f32_e32 v22, 0x3f3504f3, v3
	v_fma_f32 v25, v24, s71, -v26
	v_fma_f32 v24, v24, s70, -v26
	v_mov_b32_e32 v7, v6
	v_mov_b32_e32 v3, v2
	v_mov_b32_e32 v13, v12
	v_mov_b32_e32 v5, v4
	v_mov_b32_e32 v19, v18
	v_mov_b32_e32 v9, v8
	v_mov_b32_e32 v11, v10
	v_mov_b32_e32 v26, v25
	v_mov_b32_e32 v27, v25
	v_mov_b32_e32 v15, v14
	v_mov_b32_e32 v21, v20
	v_mov_b32_e32 v17, v16
	v_mov_b32_e32 v23, v22
	v_pk_mov_b32 v[28:29], v[24:25], v[24:25] op_sel:[1,0]
	v_lshlrev_b32_e32 v32, 3, v30
	s_mov_b64 s[14:15], 0
